# final RMS norm loop: gain quarters loaded once, next row prefetched while the current row is reduced and scaled, stores not waited for (hipcc's reduction code verbatim)
# speedup vs baseline: 1.0024x; 1.0024x over previous
; __device__ __forceinline__ int ltid(int wvs) { int t = (wvs << 6) | (int)__builtin_amdgcn_mbcnt_hi(~0u, __builtin_amdgcn_mbcnt_lo(~0u, 0u)); asm volatile("" : "+v"(t)); return t; }
; __device__ __forceinline__ int lbid() { int b = __builtin_amdgcn_workgroup_id_x(); asm volatile("" : "+s"(b)); return b; }
; __device__ __forceinline__ void phase_final(const int wvs, const Params& p) {
;   const int lane = ltid(wvs) & 63, gw = lbid() * 8 + (ltid(wvs) >> 6); const float* gain = p.in[I_NFIN];
;   for (int row = gw; row < NB * 4096; row += NWAVES) { float* xr = p.out + (size_t)row * DM; f32x4 v[4]; float ss = 0.f;
; #pragma unroll
;     for (int i = 0; i < 4; ++i) { v[i] = *(const f32x4*)(xr + lane * 4 + 256 * i); ss += v[i][0] * v[i][0] + v[i][1] * v[i][1] + v[i][2] * v[i][2] + v[i][3] * v[i][3]; }
;     ss = wave_sum(ss); const float rs = rsqrtf(ss * (1.0f / DM) + 1e-6f);
; #pragma unroll
;     for (int i = 0; i < 4; ++i) { const int k = lane * 4 + 256 * i; const f32x4 g4 = *(const f32x4*)(gain + k); *(f32x4*)(xr + k) = v[i] * rs * g4; }
;   }
.LBB0_1950:
	v_mov_b32_e32 v5, v193
	s_lshl_b32 s2, s28, 3
	s_movk_i32 s3, 0x4000
	v_ashrrev_i32_e32 v2, 6, v193
	v_add_u32_e32 v3, s2, v2
	v_cmp_gt_i32_e32 vcc, s3, v3
	s_and_saveexec_b64 s[4:5], vcc
	s_cbranch_execz .LBB0_1953
	s_load_dwordx2 s[4:5], s[0:1], 0x40
	s_load_dwordx2 s[6:7], s[0:1], 0x130
	v_add_u32_e32 v4, 0xfffff800, v3
	v_ashrrev_i32_e32 v3, 31, v2
	s_ashr_i32 s3, s2, 31
	v_lshl_add_u64 v[2:3], v[2:3], 0, s[2:3]
	v_lshlrev_b32_e32 v0, 4, v5
	v_lshlrev_b64 v[2:3], 12, v[2:3]
	v_and_b32_e32 v5, 63, v5
	v_lshl_or_b32 v2, v5, 4, v2
	v_mov_b32_e32 v1, 0
	v_and_b32_e32 v0, 0x3f0, v0
	s_waitcnt lgkmcnt(0)
	v_lshl_add_u64 v[2:3], s[6:7], 0, v[2:3]
	s_mov_b64 s[0:1], 0x800
	v_lshl_add_u64 v[0:1], s[4:5], 0, v[0:1]
	v_lshl_add_u64 v[2:3], v[2:3], 0, s[0:1]
	s_mov_b64 s[0:1], 0
	v_mov_b32_e32 v5, 0x358637bd
	s_mov_b32 s4, 0x800000
	s_mov_b64 s[2:3], 0x800000
	s_movk_i32 s5, 0x37ff
	global_load_dwordx4 v[44:47], v[0:1], off
	global_load_dwordx4 v[48:51], v[0:1], off offset:1024
	global_load_dwordx4 v[52:55], v[0:1], off offset:2048
	global_load_dwordx4 v[56:59], v[0:1], off offset:3072
	global_load_dwordx4 v[60:63], v[2:3], off offset:-2048
	global_load_dwordx4 v[64:67], v[2:3], off offset:-1024
	global_load_dwordx4 v[68:71], v[2:3], off
	global_load_dwordx4 v[72:75], v[2:3], off offset:1024
	s_mov_b32 s5, 8
	s_waitcnt vmcnt(0)
.LBB0_1952:
	s_waitcnt vmcnt(4)
	v_mov_b64_e32 v[6:7], v[60:61]
	v_mov_b64_e32 v[8:9], v[62:63]
	v_mov_b64_e32 v[10:11], v[64:65]
	v_mov_b64_e32 v[12:13], v[66:67]
	v_mov_b64_e32 v[14:15], v[68:69]
	v_mov_b64_e32 v[16:17], v[70:71]
	v_mov_b64_e32 v[18:19], v[72:73]
	v_mov_b64_e32 v[20:21], v[74:75]
	s_sub_u32 s5, s5, 1
	s_cmp_eq_u32 s5, 0
	s_cbranch_scc1 .Lfin_nopf
	v_lshl_add_u64 v[42:43], v[2:3], 0, s[2:3]
	global_load_dwordx4 v[60:63], v[42:43], off offset:-2048
	global_load_dwordx4 v[64:67], v[42:43], off offset:-1024
	global_load_dwordx4 v[68:71], v[42:43], off
	global_load_dwordx4 v[72:75], v[42:43], off offset:1024
.Lfin_nopf:
	v_mov_b32_e32 v28, v7
	v_mov_b32_e32 v29, v11
	v_mov_b32_e32 v26, v6
	v_mov_b32_e32 v27, v10
	v_mov_b32_e32 v36, v15
	v_mov_b32_e32 v37, v19
	v_pk_mul_f32 v[28:29], v[28:29], v[28:29]
	v_mov_b32_e32 v30, v8
	v_mov_b32_e32 v31, v12
	v_mov_b32_e32 v34, v14
	v_mov_b32_e32 v35, v18
	v_pk_mul_f32 v[36:37], v[36:37], v[36:37]
	v_pk_fma_f32 v[26:27], v[26:27], v[26:27], v[28:29]
	v_mov_b32_e32 v32, v9
	v_mov_b32_e32 v33, v13
	v_mov_b32_e32 v38, v16
	v_mov_b32_e32 v39, v20
	v_pk_fma_f32 v[28:29], v[34:35], v[34:35], v[36:37]
	v_pk_fma_f32 v[26:27], v[30:31], v[30:31], v[26:27]
	v_mov_b32_e32 v40, v17
	v_mov_b32_e32 v41, v21
	v_pk_fma_f32 v[28:29], v[38:39], v[38:39], v[28:29]
	v_pk_fma_f32 v[26:27], v[32:33], v[32:33], v[26:27]
	v_pk_fma_f32 v[28:29], v[40:41], v[40:41], v[28:29]
	v_add_f32_e32 v26, v26, v27
	v_add_f32_e32 v26, v26, v28
	v_add_f32_e32 v26, v26, v29
	s_nop 1
	v_add_f32_dpp v26, v26, v26 quad_perm:[1,0,3,2] row_mask:0xf bank_mask:0xf bound_ctrl:1
	s_nop 1
	v_add_f32_dpp v26, v26, v26 quad_perm:[2,3,0,1] row_mask:0xf bank_mask:0xf bound_ctrl:1
	s_nop 1
	v_add_f32_dpp v26, v26, v26 row_half_mirror row_mask:0xf bank_mask:0xf bound_ctrl:1
	s_nop 1
	v_add_f32_dpp v26, v26, v26 row_mirror row_mask:0xf bank_mask:0xf bound_ctrl:1
	s_nop 0
	v_readlane_b32 s8, v26, 16
	v_readlane_b32 s9, v26, 48
	v_readlane_b32 s6, v26, 0
	v_readlane_b32 s7, v26, 32
	v_mov_b32_e32 v26, s8
	v_mov_b32_e32 v27, s9
	v_pk_add_f32 v[26:27], s[6:7], v[26:27]
	s_nop 0
	v_add_f32_e32 v26, v26, v27
	v_fmamk_f32 v26, v26, 0x3a800000, v5
	v_mul_f32_e32 v27, 0x4b800000, v26
	v_cmp_gt_f32_e32 vcc, s4, v26
	s_nop 1
	v_cndmask_b32_e32 v26, v26, v27, vcc
	v_rsq_f32_e32 v26, v26
	s_nop 0
	v_mul_f32_e32 v27, 0x45800000, v26
	v_cndmask_b32_e32 v26, v26, v27, vcc
	v_pk_mul_f32 v[6:7], v[6:7], v[26:27] op_sel_hi:[1,0]
	v_pk_mul_f32 v[8:9], v[8:9], v[26:27] op_sel_hi:[1,0]
	v_pk_mul_f32 v[6:7], v[44:45], v[6:7]
	v_pk_mul_f32 v[8:9], v[46:47], v[8:9]
	global_store_dwordx4 v[2:3], v[6:9], off offset:-2048
	v_pk_mul_f32 v[10:11], v[10:11], v[26:27] op_sel_hi:[1,0]
	v_pk_mul_f32 v[12:13], v[12:13], v[26:27] op_sel_hi:[1,0]
	v_pk_mul_f32 v[10:11], v[48:49], v[10:11]
	v_pk_mul_f32 v[12:13], v[50:51], v[12:13]
	global_store_dwordx4 v[2:3], v[10:13], off offset:-1024
	v_pk_mul_f32 v[14:15], v[14:15], v[26:27] op_sel_hi:[1,0]
	v_pk_mul_f32 v[16:17], v[16:17], v[26:27] op_sel_hi:[1,0]
	v_pk_mul_f32 v[14:15], v[52:53], v[14:15]
	v_pk_mul_f32 v[16:17], v[54:55], v[16:17]
	global_store_dwordx4 v[2:3], v[14:17], off
	v_pk_mul_f32 v[18:19], v[18:19], v[26:27] op_sel_hi:[1,0]
	v_pk_mul_f32 v[20:21], v[20:21], v[26:27] op_sel_hi:[1,0]
	v_pk_mul_f32 v[18:19], v[56:57], v[18:19]
	v_pk_mul_f32 v[20:21], v[58:59], v[20:21]
	global_store_dwordx4 v[2:3], v[18:21], off offset:1024
	v_lshl_add_u64 v[2:3], v[2:3], 0, s[2:3]
	s_cmp_lg_u32 s5, 0
	s_cbranch_scc1 .LBB0_1952
